# attention: running-max reference enters through the first QK MFMA's C operand (removes 64 v_sub per tile); LDS address regs moved to rematerialised lane constants
# speedup vs baseline: 1.0212x; 1.0016x over previous
.LBB0_674:
	v_mov_b32_e32 v225, 0
	v_mov_b32_e32 v226, 0x358637bd
	v_mov_b32_e32 v227, v234
	v_and_b32_e32 v235, 31, v234
	v_bfe_u32 v237, v234, 5, 1
	v_lshlrev_b32_e32 v237, 2, v237
	v_and_b32_e32 v2, 64, v234
	v_xor_b32_e32 v1, 32, v234
	v_add_u32_e32 v2, 64, v2
	v_cmp_lt_i32_e32 vcc, v1, v2
	v_lshlrev_b32_e32 v89, 2, v237
	s_add_i32 s81, s81, s80
	v_cndmask_b32_e32 v1, v234, v1, vcc
	v_lshlrev_b32_e32 v1, 2, v1
	ds_bpermute_b32 v2, v1, v243
	v_or_b32_e32 v88, s81, v235
	v_lshlrev_b32_e32 v224, 1, v237
	v_lshl_add_u64 v[86:87], s[82:83], 0, v[224:225]
	s_mov_b64 s[8:9], 0
	s_waitcnt lgkmcnt(0)
	v_add_f32_e32 v2, v243, v2
	v_div_scale_f32 v3, s[6:7], v2, v2, 1.0
	v_rcp_f32_e32 v4, v3
	v_readlane_b32 s73, v254, 20
	v_fma_f32 v5, -v3, v4, 1.0
	v_fmac_f32_e32 v4, v5, v4
	v_div_scale_f32 v5, vcc, 1.0, v2, 1.0
	v_mul_f32_e32 v6, v5, v4
	v_fma_f32 v7, -v3, v6, v5
	v_fmac_f32_e32 v6, v7, v4
	v_fma_f32 v3, -v3, v6, v5
	v_div_fmas_f32 v3, v3, v4, v6
	v_div_fixup_f32 v10, v3, v2, 1.0
	v_pk_mul_f32 v[80:81], v[74:75], v[10:11] op_sel_hi:[1,0]
	v_pk_mul_f32 v[84:85], v[58:59], v[10:11] op_sel_hi:[1,0]
	v_pk_mul_f32 v[2:3], v[80:81], v[80:81]
	v_pk_mul_f32 v[14:15], v[76:77], v[10:11] op_sel_hi:[1,0]
	v_pk_fma_f32 v[94:95], v[84:85], v[84:85], v[2:3]
	v_pk_mul_f32 v[74:75], v[60:61], v[10:11] op_sel_hi:[1,0]
	v_pk_mul_f32 v[2:3], v[14:15], v[14:15]
	v_pk_mul_f32 v[76:77], v[78:79], v[10:11] op_sel_hi:[1,0]
	v_pk_fma_f32 v[96:97], v[74:75], v[74:75], v[2:3]
	v_pk_mul_f32 v[82:83], v[62:63], v[10:11] op_sel_hi:[1,0]
	v_pk_mul_f32 v[2:3], v[76:77], v[76:77]
	v_pk_mul_f32 v[100:101], v[50:51], v[10:11] op_sel_hi:[1,0]
	v_pk_fma_f32 v[98:99], v[82:83], v[82:83], v[2:3]
	v_pk_mul_f32 v[102:103], v[48:49], v[10:11] op_sel_hi:[1,0]
	global_load_dwordx4 v[58:61], v89, s[4:5]
	global_load_dwordx4 v[6:9], v89, s[4:5] offset:32
	global_load_dwordx4 v[48:51], v89, s[4:5] offset:128
	global_load_dwordx4 v[2:5], v89, s[4:5] offset:160
	v_pk_mul_f32 v[70:71], v[70:71], v[10:11] op_sel_hi:[1,0]
	v_pk_mul_f32 v[104:105], v[54:55], v[10:11] op_sel_hi:[1,0]
	v_pk_mul_f32 v[12:13], v[70:71], v[70:71]
	v_pk_mul_f32 v[72:73], v[72:73], v[10:11] op_sel_hi:[1,0]
	v_pk_fma_f32 v[106:107], v[104:105], v[104:105], v[12:13]
	ds_bpermute_b32 v12, v1, v239
	v_pk_mul_f32 v[78:79], v[66:67], v[10:11] op_sel_hi:[1,0]
	v_pk_mul_f32 v[90:91], v[64:65], v[10:11] op_sel_hi:[1,0]
	v_pk_mul_f32 v[92:93], v[68:69], v[10:11] op_sel_hi:[1,0]
	v_pk_mul_f32 v[108:109], v[52:53], v[10:11] op_sel_hi:[1,0]
	v_pk_mul_f32 v[110:111], v[56:57], v[10:11] op_sel_hi:[1,0]
	v_pk_mul_f32 v[10:11], v[72:73], v[72:73]
	s_waitcnt lgkmcnt(0)
	v_add_f32_e32 v56, v239, v12
	v_pk_fma_f32 v[112:113], v[110:111], v[110:111], v[10:11]
	global_load_dwordx4 v[66:69], v89, s[4:5] offset:64
	global_load_dwordx4 v[52:55], v89, s[4:5] offset:96
	global_load_dwordx4 v[62:65], v89, s[4:5] offset:192
	global_load_dwordx4 v[10:13], v89, s[4:5] offset:224
	v_div_scale_f32 v57, s[6:7], v56, v56, 1.0
	v_rcp_f32_e32 v114, v57
	v_mov_b32_e32 v123, v78
	v_mov_b32_e32 v125, v79
	v_mov_b32_e32 v127, v90
	v_fma_f32 v89, -v57, v114, 1.0
	v_fmac_f32_e32 v114, v89, v114
	v_div_scale_f32 v89, vcc, 1.0, v56, 1.0
	v_mul_f32_e32 v115, v89, v114
	v_fma_f32 v116, -v57, v115, v89
	v_fmac_f32_e32 v115, v116, v114
	v_fma_f32 v57, -v57, v115, v89
	v_div_fmas_f32 v57, v57, v114, v115
	v_div_fixup_f32 v114, v57, v56, 1.0
	v_pk_mul_f32 v[34:35], v[34:35], v[114:115] op_sel_hi:[1,0]
	v_pk_mul_f32 v[32:33], v[32:33], v[114:115] op_sel_hi:[1,0]
	v_pk_mul_f32 v[18:19], v[18:19], v[114:115] op_sel_hi:[1,0]
	v_mov_b32_e32 v122, v34
	v_mov_b32_e32 v124, v35
	v_pk_mul_f32 v[16:17], v[16:17], v[114:115] op_sel_hi:[1,0]
	v_pk_mul_f32 v[122:123], v[122:123], v[122:123]
	v_pk_mul_f32 v[124:125], v[124:125], v[124:125]
	v_mov_b32_e32 v126, v32
	v_mov_b32_e32 v128, v33
	v_mov_b32_e32 v129, v91
	v_mov_b32_e32 v130, v18
	v_mov_b32_e32 v131, v100
	v_mov_b32_e32 v132, v19
	v_mov_b32_e32 v133, v101
	v_pk_mul_f32 v[126:127], v[126:127], v[126:127]
	v_pk_mul_f32 v[128:129], v[128:129], v[128:129]
	v_pk_fma_f32 v[122:123], v[130:131], v[130:131], v[122:123]
	v_pk_fma_f32 v[124:125], v[132:133], v[132:133], v[124:125]
	v_mov_b32_e32 v130, v16
	v_mov_b32_e32 v131, v102
	v_mov_b32_e32 v132, v17
	v_mov_b32_e32 v133, v103
	v_pk_fma_f32 v[126:127], v[130:131], v[130:131], v[126:127]
	v_pk_fma_f32 v[128:129], v[132:133], v[132:133], v[128:129]
	v_pk_mul_f32 v[36:37], v[36:37], v[114:115] op_sel_hi:[1,0]
	v_pk_add_f32 v[126:127], v[126:127], v[128:129]
	v_pk_mul_f32 v[42:43], v[42:43], v[114:115] op_sel_hi:[1,0]
	v_pk_add_f32 v[122:123], v[122:123], v[126:127]
	v_pk_mul_f32 v[20:21], v[20:21], v[114:115] op_sel_hi:[1,0]
	v_pk_add_f32 v[122:123], v[124:125], v[122:123]
	v_mov_b32_e32 v124, v36
	v_mov_b32_e32 v125, v92
	v_pk_mul_f32 v[56:57], v[26:27], v[114:115] op_sel_hi:[1,0]
	v_pk_mul_f32 v[26:27], v[42:43], v[42:43]
	v_pk_mul_f32 v[38:39], v[38:39], v[114:115] op_sel_hi:[1,0]
	v_pk_mul_f32 v[124:125], v[124:125], v[124:125]
	v_mov_b32_e32 v126, v37
	v_mov_b32_e32 v127, v93
	v_mov_b32_e32 v128, v20
	v_mov_b32_e32 v129, v108
	v_pk_fma_f32 v[116:117], v[56:57], v[56:57], v[26:27]
	v_pk_mul_f32 v[26:27], v[44:45], v[114:115] op_sel_hi:[1,0]
	v_pk_mul_f32 v[22:23], v[22:23], v[114:115] op_sel_hi:[1,0]
	v_pk_mul_f32 v[120:121], v[38:39], v[38:39]
	v_pk_mul_f32 v[126:127], v[126:127], v[126:127]
	v_mov_b32_e32 v130, v21
	v_mov_b32_e32 v131, v109
	v_pk_fma_f32 v[124:125], v[128:129], v[128:129], v[124:125]
	v_pk_mul_f32 v[28:29], v[28:29], v[114:115] op_sel_hi:[1,0]
	v_pk_mul_f32 v[44:45], v[26:27], v[26:27]
	v_pk_fma_f32 v[120:121], v[22:23], v[22:23], v[120:121]
	v_pk_fma_f32 v[126:127], v[130:131], v[130:131], v[126:127]
	v_pk_add_f32 v[122:123], v[124:125], v[122:123]
	v_pk_mul_f32 v[40:41], v[40:41], v[114:115] op_sel_hi:[1,0]
	v_pk_fma_f32 v[118:119], v[28:29], v[28:29], v[44:45]
	v_pk_mul_f32 v[44:45], v[30:31], v[114:115] op_sel_hi:[1,0]
	v_pk_mul_f32 v[30:31], v[46:47], v[114:115] op_sel_hi:[1,0]
	v_pk_add_f32 v[122:123], v[126:127], v[122:123]
	v_mov_b32_e32 v124, v120
	v_mov_b32_e32 v125, v106
	v_pk_mul_f32 v[24:25], v[24:25], v[114:115] op_sel_hi:[1,0]
	v_pk_mul_f32 v[114:115], v[40:41], v[40:41]
	v_pk_add_f32 v[122:123], v[124:125], v[122:123]
	v_mov_b32_e32 v106, v121
	v_pk_fma_f32 v[114:115], v[24:25], v[24:25], v[114:115]
	v_pk_add_f32 v[106:107], v[106:107], v[122:123]
	v_mov_b32_e32 v120, v114
	v_mov_b32_e32 v121, v112
	v_pk_add_f32 v[106:107], v[120:121], v[106:107]
	v_mov_b32_e32 v112, v115
	v_pk_add_f32 v[106:107], v[112:113], v[106:107]
	v_mov_b32_e32 v112, v116
	v_mov_b32_e32 v113, v94
	v_pk_add_f32 v[106:107], v[112:113], v[106:107]
	v_mov_b32_e32 v94, v117
	v_pk_mul_f32 v[46:47], v[30:31], v[30:31]
	v_pk_add_f32 v[94:95], v[94:95], v[106:107]
	v_mov_b32_e32 v106, v118
	v_mov_b32_e32 v107, v96
	v_pk_fma_f32 v[46:47], v[44:45], v[44:45], v[46:47]
	v_pk_add_f32 v[94:95], v[106:107], v[94:95]
	v_mov_b32_e32 v96, v119
	v_pk_add_f32 v[94:95], v[96:97], v[94:95]
	v_mov_b32_e32 v96, v46
	v_mov_b32_e32 v97, v98
	v_pk_add_f32 v[94:95], v[96:97], v[94:95]
	v_mov_b32_e32 v98, v47
	v_pk_add_f32 v[46:47], v[98:99], v[94:95]
	ds_bpermute_b32 v95, v1, v47
	ds_bpermute_b32 v94, v1, v46
	s_mov_b32 s6, 0x3c800000
	v_ashrrev_i32_e32 v89, 31, v88
	v_lshlrev_b64 v[96:97], 11, v[88:89]
	v_or_b32_e32 v88, 32, v88
	s_waitcnt lgkmcnt(0)
	v_pk_add_f32 v[46:47], v[46:47], v[94:95]
	v_ashrrev_i32_e32 v89, 31, v88
	v_pk_fma_f32 v[46:47], v[46:47], s[6:7], v[226:227] op_sel_hi:[1,0,0]
	s_mov_b32 s6, 0x800000
	v_mul_f32_e32 v1, 0x4b800000, v47
	v_cmp_gt_f32_e32 vcc, s6, v47
	v_lshlrev_b64 v[88:89], 11, v[88:89]
	v_lshl_add_u64 v[96:97], v[86:87], 0, v[96:97]
	v_cndmask_b32_e32 v1, v47, v1, vcc
	v_rsq_f32_e32 v1, v1
	v_lshl_add_u64 v[86:87], v[86:87], 0, v[88:89]
	v_mul_f32_e32 v47, 0x45800000, v1
	v_cndmask_b32_e32 v88, v1, v47, vcc
	v_pk_mul_f32 v[94:95], v[102:103], v[88:89] op_sel_hi:[1,0]
	v_pk_mul_f32 v[98:99], v[100:101], v[88:89] op_sel_hi:[1,0]
	v_pk_mul_f32 v[90:91], v[90:91], v[88:89] op_sel_hi:[1,0]
	v_pk_mul_f32 v[78:79], v[78:79], v[88:89] op_sel_hi:[1,0]
	s_waitcnt vmcnt(7)
	v_pk_mul_f32 v[94:95], v[58:59], v[94:95]
	v_pk_mul_f32 v[98:99], v[60:61], v[98:99]
	s_waitcnt vmcnt(5)
	v_pk_mul_f32 v[90:91], v[48:49], v[90:91]
	v_pk_mul_f32 v[78:79], v[50:51], v[78:79]
	v_cvt_pk_bf16_f32 v94, v94, v95
	v_cvt_pk_bf16_f32 v95, v98, v99
	v_cvt_pk_bf16_f32 v90, v90, v91
	v_cvt_pk_bf16_f32 v91, v78, v79
	global_store_dwordx2 v[96:97], v[94:95], off
	global_store_dwordx2 v[96:97], v[90:91], off offset:64
	v_pk_mul_f32 v[78:79], v[108:109], v[88:89] op_sel_hi:[1,0]
	v_pk_mul_f32 v[90:91], v[104:105], v[88:89] op_sel_hi:[1,0]
	v_pk_mul_f32 v[78:79], v[6:7], v[78:79]
	v_pk_mul_f32 v[90:91], v[8:9], v[90:91]
	v_cvt_pk_bf16_f32 v78, v78, v79
	v_cvt_pk_bf16_f32 v79, v90, v91
	v_pk_mul_f32 v[90:91], v[92:93], v[88:89] op_sel_hi:[1,0]
	v_pk_mul_f32 v[70:71], v[70:71], v[88:89] op_sel_hi:[1,0]
	s_waitcnt vmcnt(6)
	v_pk_mul_f32 v[90:91], v[2:3], v[90:91]
	v_pk_mul_f32 v[70:71], v[4:5], v[70:71]
	v_cvt_pk_bf16_f32 v90, v90, v91
	v_cvt_pk_bf16_f32 v91, v70, v71
	global_store_dwordx2 v[96:97], v[78:79], off offset:16
	global_store_dwordx2 v[96:97], v[90:91], off offset:80
	v_pk_mul_f32 v[70:71], v[110:111], v[88:89] op_sel_hi:[1,0]
	v_pk_mul_f32 v[78:79], v[84:85], v[88:89] op_sel_hi:[1,0]
	s_waitcnt vmcnt(7)
	v_pk_mul_f32 v[70:71], v[66:67], v[70:71]
	v_pk_mul_f32 v[78:79], v[68:69], v[78:79]
	v_cvt_pk_bf16_f32 v70, v70, v71
	v_cvt_pk_bf16_f32 v71, v78, v79
	v_pk_mul_f32 v[72:73], v[72:73], v[88:89] op_sel_hi:[1,0]
	v_pk_mul_f32 v[78:79], v[80:81], v[88:89] op_sel_hi:[1,0]
	s_waitcnt vmcnt(5)
	v_pk_mul_f32 v[72:73], v[62:63], v[72:73]
	v_pk_mul_f32 v[78:79], v[64:65], v[78:79]
	v_mul_f32_e32 v1, 0x4b800000, v46
	v_cmp_gt_f32_e32 vcc, s6, v46
	v_cvt_pk_bf16_f32 v72, v72, v73
	v_cvt_pk_bf16_f32 v73, v78, v79
	v_cndmask_b32_e32 v1, v46, v1, vcc
	global_store_dwordx2 v[96:97], v[70:71], off offset:32
	global_store_dwordx2 v[96:97], v[72:73], off offset:96
	v_pk_mul_f32 v[70:71], v[74:75], v[88:89] op_sel_hi:[1,0]
	v_pk_mul_f32 v[72:73], v[82:83], v[88:89] op_sel_hi:[1,0]
	v_rsq_f32_e32 v1, v1
	v_pk_mul_f32 v[70:71], v[52:53], v[70:71]
	v_pk_mul_f32 v[72:73], v[54:55], v[72:73]
	v_pk_mul_f32 v[14:15], v[14:15], v[88:89] op_sel_hi:[1,0]
	v_cvt_pk_bf16_f32 v70, v70, v71
	v_cvt_pk_bf16_f32 v71, v72, v73
	s_waitcnt vmcnt(6)
	v_pk_mul_f32 v[14:15], v[10:11], v[14:15]
	v_pk_mul_f32 v[72:73], v[76:77], v[88:89] op_sel_hi:[1,0]
	v_cvt_pk_bf16_f32 v14, v14, v15
	v_pk_mul_f32 v[72:73], v[12:13], v[72:73]
	s_nop 0
	v_cvt_pk_bf16_f32 v15, v72, v73
	global_store_dwordx2 v[96:97], v[70:71], off offset:48
	global_store_dwordx2 v[96:97], v[14:15], off offset:112
	v_mul_f32_e32 v14, 0x45800000, v1
	v_cndmask_b32_e32 v14, v1, v14, vcc
	v_pk_mul_f32 v[16:17], v[16:17], v[14:15] op_sel_hi:[1,0]
	v_pk_mul_f32 v[18:19], v[18:19], v[14:15] op_sel_hi:[1,0]
	v_pk_mul_f32 v[16:17], v[58:59], v[16:17]
	v_pk_mul_f32 v[18:19], v[60:61], v[18:19]
	v_cvt_pk_bf16_f32 v16, v16, v17
	v_cvt_pk_bf16_f32 v17, v18, v19
	v_pk_mul_f32 v[18:19], v[32:33], v[14:15] op_sel_hi:[1,0]
	v_pk_mul_f32 v[32:33], v[34:35], v[14:15] op_sel_hi:[1,0]
	v_pk_mul_f32 v[18:19], v[48:49], v[18:19]
	v_pk_mul_f32 v[32:33], v[50:51], v[32:33]
	v_cvt_pk_bf16_f32 v18, v18, v19
	v_cvt_pk_bf16_f32 v19, v32, v33
	global_store_dwordx2 v[86:87], v[16:17], off
	global_store_dwordx2 v[86:87], v[18:19], off offset:64
	v_pk_mul_f32 v[16:17], v[20:21], v[14:15] op_sel_hi:[1,0]
	s_and_b64 vcc, exec, s[92:93]
	v_pk_mul_f32 v[6:7], v[6:7], v[16:17]
	v_pk_mul_f32 v[16:17], v[22:23], v[14:15] op_sel_hi:[1,0]
	v_cvt_pk_bf16_f32 v6, v6, v7
	v_pk_mul_f32 v[8:9], v[8:9], v[16:17]
	s_nop 0
	v_cvt_pk_bf16_f32 v7, v8, v9
	v_pk_mul_f32 v[8:9], v[36:37], v[14:15] op_sel_hi:[1,0]
	s_nop 0
	v_pk_mul_f32 v[2:3], v[2:3], v[8:9]
	v_pk_mul_f32 v[8:9], v[38:39], v[14:15] op_sel_hi:[1,0]
	v_cvt_pk_bf16_f32 v2, v2, v3
	v_pk_mul_f32 v[4:5], v[4:5], v[8:9]
	s_nop 0
	v_cvt_pk_bf16_f32 v3, v4, v5
	global_store_dwordx2 v[86:87], v[6:7], off offset:16
	global_store_dwordx2 v[86:87], v[2:3], off offset:80
	v_pk_mul_f32 v[2:3], v[24:25], v[14:15] op_sel_hi:[1,0]
	v_pk_mul_f32 v[4:5], v[56:57], v[14:15] op_sel_hi:[1,0]
	v_pk_mul_f32 v[2:3], v[66:67], v[2:3]
	v_pk_mul_f32 v[4:5], v[68:69], v[4:5]
	v_cvt_pk_bf16_f32 v2, v2, v3
	v_cvt_pk_bf16_f32 v3, v4, v5
	v_pk_mul_f32 v[4:5], v[40:41], v[14:15] op_sel_hi:[1,0]
	v_pk_mul_f32 v[6:7], v[42:43], v[14:15] op_sel_hi:[1,0]
	v_pk_mul_f32 v[4:5], v[62:63], v[4:5]
	v_pk_mul_f32 v[6:7], v[64:65], v[6:7]
	v_cvt_pk_bf16_f32 v4, v4, v5
	v_cvt_pk_bf16_f32 v5, v6, v7
	global_store_dwordx2 v[86:87], v[2:3], off offset:32
	global_store_dwordx2 v[86:87], v[4:5], off offset:96
	v_pk_mul_f32 v[2:3], v[28:29], v[14:15] op_sel_hi:[1,0]
	v_pk_mul_f32 v[4:5], v[44:45], v[14:15] op_sel_hi:[1,0]
	v_pk_mul_f32 v[2:3], v[52:53], v[2:3]
	v_pk_mul_f32 v[4:5], v[54:55], v[4:5]
	v_cvt_pk_bf16_f32 v2, v2, v3
	v_cvt_pk_bf16_f32 v3, v4, v5
	v_pk_mul_f32 v[4:5], v[26:27], v[14:15] op_sel_hi:[1,0]
	v_pk_mul_f32 v[6:7], v[30:31], v[14:15] op_sel_hi:[1,0]
	v_pk_mul_f32 v[4:5], v[10:11], v[4:5]
	v_pk_mul_f32 v[6:7], v[12:13], v[6:7]
	v_cvt_pk_bf16_f32 v4, v4, v5
	v_cvt_pk_bf16_f32 v5, v6, v7
	global_store_dwordx2 v[86:87], v[2:3], off offset:48
	global_store_dwordx2 v[86:87], v[4:5], off offset:112
	s_cbranch_vccnz .LBB0_672

.LBB0_688:
	s_add_i32 s73, s95, 0
	s_cmp_lg_u32 s90, 0
	s_cbranch_scc1 .La_tinit_done
	v_mov_b32_e32 v100, 0
	v_mov_b32_e32 v101, 0
	v_mov_b32_e32 v102, 0
	v_mov_b32_e32 v103, 0
	v_mov_b32_e32 v104, 0
	v_mov_b32_e32 v105, 0
	v_mov_b32_e32 v106, 0
	v_mov_b32_e32 v107, 0
	v_mov_b32_e32 v108, 0
	v_mov_b32_e32 v109, 0
	v_mov_b32_e32 v110, 0
	v_mov_b32_e32 v111, 0
	v_mov_b32_e32 v112, 0
	v_mov_b32_e32 v113, 0
	v_mov_b32_e32 v114, 0
	v_mov_b32_e32 v115, 0
	v_mov_b32_e32 v0, 0
	v_mov_b32_e32 v1, 0
	v_mov_b32_e32 v2, 0
	v_mov_b32_e32 v3, 0
	v_mov_b32_e32 v4, 0
	v_mov_b32_e32 v5, 0
	v_mov_b32_e32 v6, 0
	v_mov_b32_e32 v7, 0
	v_mov_b32_e32 v8, 0
	v_mov_b32_e32 v9, 0
	v_mov_b32_e32 v10, 0
	v_mov_b32_e32 v11, 0
	v_mov_b32_e32 v12, 0
	v_mov_b32_e32 v13, 0
	v_mov_b32_e32 v14, 0
	v_mov_b32_e32 v15, 0
.La_tinit_done:
	v_add3_u32 v235, s73, v241, v224
	v_add3_u32 v237, s73, v242, v224
	ds_read_b128 v[96:99], v235
	ds_read_b128 v[246:249], v235 offset:6656
	ds_read_b128 v[250:253], v235 offset:32
	s_waitcnt lgkmcnt(2)
	v_mfma_f32_32x32x16_bf16 v[148:163], v[96:99], v[176:179], v[100:115]
	ds_read_b128 v[96:99], v235 offset:6688
	s_waitcnt lgkmcnt(2)
	v_mfma_f32_32x32x16_bf16 v[80:95], v[246:249], v[176:179], v[100:115]
	ds_read_b128 v[246:249], v235 offset:64
	s_waitcnt lgkmcnt(2)
	v_mfma_f32_32x32x16_bf16 v[148:163], v[250:253], v[180:183], v[148:163]
	ds_read_b128 v[250:253], v235 offset:6720
	s_waitcnt lgkmcnt(2)
	v_mfma_f32_32x32x16_bf16 v[80:95], v[96:99], v[180:183], v[80:95]
	ds_read_b128 v[96:99], v235 offset:96
	s_waitcnt lgkmcnt(2)
	v_mfma_f32_32x32x16_bf16 v[148:163], v[246:249], v[184:187], v[148:163]
	ds_read_b128 v[246:249], v235 offset:6752
	s_waitcnt lgkmcnt(2)
	v_mfma_f32_32x32x16_bf16 v[80:95], v[250:253], v[184:187], v[80:95]
	ds_read_b128 v[250:253], v235 offset:128
	s_waitcnt lgkmcnt(2)
	v_mfma_f32_32x32x16_bf16 v[148:163], v[96:99], v[188:191], v[148:163]
	ds_read_b128 v[96:99], v235 offset:6784
	s_waitcnt lgkmcnt(2)
	v_mfma_f32_32x32x16_bf16 v[80:95], v[246:249], v[188:191], v[80:95]
	ds_read_b128 v[246:249], v235 offset:160
	s_waitcnt lgkmcnt(2)
	v_mfma_f32_32x32x16_bf16 v[148:163], v[250:253], v[192:195], v[148:163]
	ds_read_b128 v[250:253], v235 offset:6816
	s_waitcnt lgkmcnt(2)
	v_mfma_f32_32x32x16_bf16 v[80:95], v[96:99], v[192:195], v[80:95]
	s_waitcnt lgkmcnt(1)
	v_mfma_f32_32x32x16_bf16 v[148:163], v[246:249], v[196:199], v[148:163]
	s_waitcnt lgkmcnt(0)
	v_mfma_f32_32x32x16_bf16 v[80:95], v[250:253], v[196:199], v[80:95]
	ds_read_b128 v[96:99], v235 offset:6656
	ds_read_b128 v[246:249], v235
	ds_read_b128 v[250:253], v235 offset:6688
	s_cmp_eq_u32 s74, s90
	s_cselect_b64 s[86:87], -1, 0
	s_cmp_lg_u32 s74, s90
	s_nop 9
	s_cbranch_scc1 .La_nomask0
	v_mov_b32_e32 v227, 0xff800000
	v_cndmask_b32_e64 v226, v148, v227, s[8:9]
	v_cndmask_b32_e64 v148, v226, v148, s[10:11]
	v_cndmask_b32_e64 v149, v227, v149, s[10:11]
	v_cndmask_b32_e64 v150, v150, v227, s[12:13]
	v_cndmask_b32_e64 v151, v151, v227, s[14:15]
	v_cndmask_b32_e64 v152, v152, v227, s[16:17]
	v_cndmask_b32_e64 v153, v153, v227, s[18:19]
	v_cndmask_b32_e64 v154, v154, v227, s[20:21]
	v_cndmask_b32_e64 v155, v155, v227, s[22:23]
	v_cndmask_b32_e64 v156, v156, v227, s[24:25]
	v_cndmask_b32_e64 v157, v157, v227, s[26:27]
	v_cndmask_b32_e64 v158, v158, v227, s[28:29]
	v_cndmask_b32_e64 v159, v159, v227, s[30:31]
	v_cndmask_b32_e64 v160, v160, v227, s[34:35]
	v_cndmask_b32_e64 v161, v161, v227, s[36:37]
	v_cndmask_b32_e64 v162, v162, v227, s[38:39]
	v_cndmask_b32_e64 v163, v163, v227, s[40:41]
	v_mov_b32_e32 v80, v227
	v_mov_b32_e32 v81, v227
	v_mov_b32_e32 v82, v227
	v_mov_b32_e32 v83, v227
	v_mov_b32_e32 v84, v227
	v_mov_b32_e32 v85, v227
	v_mov_b32_e32 v86, v227
	v_mov_b32_e32 v87, v227
	v_mov_b32_e32 v88, v227
	v_mov_b32_e32 v89, v227
	v_mov_b32_e32 v90, v227
	v_mov_b32_e32 v91, v227
	v_mov_b32_e32 v92, v227
	v_mov_b32_e32 v93, v227
	v_mov_b32_e32 v94, v227
	v_mov_b32_e32 v95, v227
	s_branch .La_max0
.La_nomask0:
.La_max0:
	v_max3_f32 v225, v148, v150, v152
	v_max3_f32 v226, v149, v151, v153
	v_max3_f32 v225, v225, v154, v156
	v_max3_f32 v226, v226, v155, v157
	v_max3_f32 v225, v225, v158, v160
	v_max3_f32 v226, v226, v159, v161
	v_max3_f32 v225, v225, v162, v80
	v_max3_f32 v226, v226, v163, v81
	v_max3_f32 v225, v225, v82, v84
	v_max3_f32 v226, v226, v83, v85
	v_max3_f32 v225, v225, v86, v88
	v_max3_f32 v226, v226, v87, v89
	v_max3_f32 v225, v225, v90, v92
	v_max3_f32 v226, v226, v91, v93
	v_max_f32_e32 v225, v225, v94
	v_max_f32_e32 v226, v226, v95
	v_max_f32_e32 v225, v225, v226
	s_cmp_lg_u32 s90, 0
	s_cselect_b64 s[88:89], -1, 0
	v_mov_b32_e32 v226, v225
	s_cmp_eq_u32 s90, 0
	s_nop 0
	v_permlane32_swap_b32_e32 v225, v226
	v_max_f32_e32 v225, v225, v226
	s_cbranch_scc1 .La_resc0
	v_cmp_lt_f32_e32 vcc, s72, v225
	s_cbranch_vccz .La_qk1
	v_max_f32_e32 v225, v225, v225
	v_max_f32_e32 v225, 0, v225
.La_resc0:
	v_exp_f32_e64 v226, -v225
	v_add_f32_e32 v244, v244, v225
	v_sub_f32_e32 v148, v148, v225
	v_sub_f32_e32 v149, v149, v225
	v_sub_f32_e32 v150, v150, v225
	v_sub_f32_e32 v151, v151, v225
	v_sub_f32_e32 v152, v152, v225
	v_sub_f32_e32 v153, v153, v225
	v_sub_f32_e32 v154, v154, v225
	v_sub_f32_e32 v155, v155, v225
	v_sub_f32_e32 v156, v156, v225
	v_sub_f32_e32 v157, v157, v225
	v_sub_f32_e32 v158, v158, v225
	v_sub_f32_e32 v159, v159, v225
	v_sub_f32_e32 v160, v160, v225
	v_sub_f32_e32 v161, v161, v225
	v_sub_f32_e32 v162, v162, v225
	v_sub_f32_e32 v163, v163, v225
	v_sub_f32_e32 v80, v80, v225
	v_sub_f32_e32 v81, v81, v225
	v_sub_f32_e32 v82, v82, v225
	v_sub_f32_e32 v83, v83, v225
	v_sub_f32_e32 v84, v84, v225
	v_sub_f32_e32 v85, v85, v225
	v_sub_f32_e32 v86, v86, v225
	v_sub_f32_e32 v87, v87, v225
	v_sub_f32_e32 v88, v88, v225
	v_sub_f32_e32 v89, v89, v225
	v_sub_f32_e32 v90, v90, v225
	v_sub_f32_e32 v91, v91, v225
	v_sub_f32_e32 v92, v92, v225
	v_sub_f32_e32 v93, v93, v225
	v_sub_f32_e32 v94, v94, v225
	v_sub_f32_e32 v95, v95, v225
	v_mul_f32_e32 v243, v243, v226
	v_pk_mul_f32 v[48:49], v[48:49], v[226:227] op_sel_hi:[1,0]
	v_pk_mul_f32 v[50:51], v[50:51], v[226:227] op_sel_hi:[1,0]
	v_pk_mul_f32 v[52:53], v[52:53], v[226:227] op_sel_hi:[1,0]
	v_pk_mul_f32 v[54:55], v[54:55], v[226:227] op_sel_hi:[1,0]
	v_pk_mul_f32 v[56:57], v[56:57], v[226:227] op_sel_hi:[1,0]
	v_pk_mul_f32 v[58:59], v[58:59], v[226:227] op_sel_hi:[1,0]
	v_pk_mul_f32 v[60:61], v[60:61], v[226:227] op_sel_hi:[1,0]
	v_pk_mul_f32 v[62:63], v[62:63], v[226:227] op_sel_hi:[1,0]
	v_pk_mul_f32 v[64:65], v[64:65], v[226:227] op_sel_hi:[1,0]
	v_pk_mul_f32 v[66:67], v[66:67], v[226:227] op_sel_hi:[1,0]
	v_pk_mul_f32 v[68:69], v[68:69], v[226:227] op_sel_hi:[1,0]
	v_pk_mul_f32 v[70:71], v[70:71], v[226:227] op_sel_hi:[1,0]
	v_pk_mul_f32 v[72:73], v[72:73], v[226:227] op_sel_hi:[1,0]
	v_pk_mul_f32 v[74:75], v[74:75], v[226:227] op_sel_hi:[1,0]
	v_pk_mul_f32 v[76:77], v[76:77], v[226:227] op_sel_hi:[1,0]
	v_pk_mul_f32 v[78:79], v[78:79], v[226:227] op_sel_hi:[1,0]
	v_sub_f32_e32 v100, 0, v244
	v_mov_b32_e32 v101, v100
	v_mov_b32_e32 v102, v100
	v_mov_b32_e32 v103, v100
	v_mov_b32_e32 v104, v100
	v_mov_b32_e32 v105, v100
	v_mov_b32_e32 v106, v100
	v_mov_b32_e32 v107, v100
	v_mov_b32_e32 v108, v100
	v_mov_b32_e32 v109, v100
	v_mov_b32_e32 v110, v100
	v_mov_b32_e32 v111, v100
	v_mov_b32_e32 v112, v100
	v_mov_b32_e32 v113, v100
	v_mov_b32_e32 v114, v100
	v_mov_b32_e32 v115, v100
.La_qk1:
	s_waitcnt lgkmcnt(2)
	v_mfma_f32_32x32x16_bf16 v[132:147], v[96:99], v[200:203], v[0:15]
	ds_read_b128 v[96:99], v235 offset:32
	s_waitcnt lgkmcnt(2)
	v_mfma_f32_32x32x16_bf16 v[116:131], v[246:249], v[200:203], v[0:15]
	ds_read_b128 v[246:249], v235 offset:6720
	s_waitcnt lgkmcnt(2)
	v_mfma_f32_32x32x16_bf16 v[132:147], v[250:253], v[204:207], v[132:147]
	ds_read_b128 v[250:253], v235 offset:64
	s_waitcnt lgkmcnt(2)
	v_mfma_f32_32x32x16_bf16 v[116:131], v[96:99], v[204:207], v[116:131]
	ds_read_b128 v[96:99], v235 offset:6752
	s_waitcnt lgkmcnt(2)
	v_mfma_f32_32x32x16_bf16 v[132:147], v[246:249], v[208:211], v[132:147]
	ds_read_b128 v[246:249], v235 offset:96
	s_waitcnt lgkmcnt(2)
	v_mfma_f32_32x32x16_bf16 v[116:131], v[250:253], v[208:211], v[116:131]
	ds_read_b128 v[250:253], v235 offset:6784
	s_waitcnt lgkmcnt(2)
	v_mfma_f32_32x32x16_bf16 v[132:147], v[96:99], v[212:215], v[132:147]
	ds_read_b128 v[96:99], v235 offset:128
	s_waitcnt lgkmcnt(2)
	v_mfma_f32_32x32x16_bf16 v[116:131], v[246:249], v[212:215], v[116:131]
	ds_read_b128 v[246:249], v235 offset:6816
	s_waitcnt lgkmcnt(2)
	v_mfma_f32_32x32x16_bf16 v[132:147], v[250:253], v[216:219], v[132:147]
	ds_read_b128 v[250:253], v235 offset:160
	s_waitcnt lgkmcnt(2)
	v_mfma_f32_32x32x16_bf16 v[116:131], v[96:99], v[216:219], v[116:131]
	s_waitcnt lgkmcnt(1)
	v_mfma_f32_32x32x16_bf16 v[132:147], v[246:249], v[220:223], v[132:147]
	s_waitcnt lgkmcnt(0)
	v_mfma_f32_32x32x16_bf16 v[116:131], v[250:253], v[220:223], v[116:131]
	ds_read_b128 v[96:99], v237 offset:13312
	ds_read_b128 v[246:249], v237 offset:17920
	ds_read_b128 v[250:253], v237 offset:13344
	s_nop 10
	s_andn2_b64 vcc, exec, s[86:87]
	s_cbranch_vccnz .La_nomask1
	v_mov_b32_e32 v227, 0xff800000
	v_cndmask_b32_e64 v132, v132, v227, s[8:9]
	v_cndmask_b32_e64 v133, v133, v227, s[42:43]
	v_cndmask_b32_e64 v134, v134, v227, s[44:45]
	v_cndmask_b32_e64 v135, v135, v227, s[46:47]
	v_cndmask_b32_e64 v136, v136, v227, s[48:49]
	v_cndmask_b32_e64 v137, v137, v227, s[50:51]
	v_cndmask_b32_e64 v138, v138, v227, s[52:53]
	v_cndmask_b32_e64 v139, v139, v227, s[54:55]
	v_cndmask_b32_e64 v140, v140, v227, s[56:57]
	v_cndmask_b32_e64 v141, v141, v227, s[58:59]
	v_cndmask_b32_e64 v142, v142, v227, s[60:61]
	v_cndmask_b32_e64 v143, v143, v227, s[62:63]
	v_cndmask_b32_e64 v144, v144, v227, s[64:65]
	v_cndmask_b32_e64 v145, v145, v227, s[66:67]
	v_cndmask_b32_e64 v146, v146, v227, s[68:69]
	v_cndmask_b32_e64 v147, v147, v227, s[70:71]
.La_nomask1:
	v_max3_f32 v225, v116, v118, v120
	v_max3_f32 v226, v117, v119, v121
	v_max3_f32 v225, v225, v122, v124
	v_max3_f32 v226, v226, v123, v125
	v_max3_f32 v225, v225, v126, v128
	v_max3_f32 v226, v226, v127, v129
	v_max3_f32 v225, v225, v130, v132
	v_max3_f32 v226, v226, v131, v133
	v_max3_f32 v225, v225, v134, v136
	v_max3_f32 v226, v226, v135, v137
	v_max3_f32 v225, v225, v138, v140
	v_max3_f32 v226, v226, v139, v141
	v_max3_f32 v225, v225, v142, v144
	v_max3_f32 v226, v226, v143, v145
	v_max_f32_e32 v225, v225, v146
	v_max_f32_e32 v226, v226, v147
	v_max_f32_e32 v225, v225, v226
	s_andn2_b64 vcc, exec, s[88:89]
	v_mov_b32_e32 v226, v225
	s_nop 1
	v_permlane32_swap_b32_e32 v225, v226
	v_max_f32_e32 v225, v225, v226
	s_cbranch_vccnz .La_resc1
	v_cmp_lt_f32_e32 vcc, s72, v225
	s_cbranch_vccz .La_exp
	v_max_f32_e32 v225, v225, v225
	v_max_f32_e32 v225, 0, v225
.La_resc1:
	v_exp_f32_e64 v226, -v225
	v_add_f32_e32 v245, v245, v225
	v_sub_f32_e32 v116, v116, v225
	v_sub_f32_e32 v117, v117, v225
	v_sub_f32_e32 v118, v118, v225
	v_sub_f32_e32 v119, v119, v225
	v_sub_f32_e32 v120, v120, v225
	v_sub_f32_e32 v121, v121, v225
	v_sub_f32_e32 v122, v122, v225
	v_sub_f32_e32 v123, v123, v225
	v_sub_f32_e32 v124, v124, v225
	v_sub_f32_e32 v125, v125, v225
	v_sub_f32_e32 v126, v126, v225
	v_sub_f32_e32 v127, v127, v225
	v_sub_f32_e32 v128, v128, v225
	v_sub_f32_e32 v129, v129, v225
	v_sub_f32_e32 v130, v130, v225
	v_sub_f32_e32 v131, v131, v225
	v_sub_f32_e32 v132, v132, v225
	v_sub_f32_e32 v133, v133, v225
	v_sub_f32_e32 v134, v134, v225
	v_sub_f32_e32 v135, v135, v225
	v_sub_f32_e32 v136, v136, v225
	v_sub_f32_e32 v137, v137, v225
	v_sub_f32_e32 v138, v138, v225
	v_sub_f32_e32 v139, v139, v225
	v_sub_f32_e32 v140, v140, v225
	v_sub_f32_e32 v141, v141, v225
	v_sub_f32_e32 v142, v142, v225
	v_sub_f32_e32 v143, v143, v225
	v_sub_f32_e32 v144, v144, v225
	v_sub_f32_e32 v145, v145, v225
	v_sub_f32_e32 v146, v146, v225
	v_sub_f32_e32 v147, v147, v225
	v_mul_f32_e32 v239, v239, v226
	v_pk_mul_f32 v[16:17], v[16:17], v[226:227] op_sel_hi:[1,0]
	v_pk_mul_f32 v[18:19], v[18:19], v[226:227] op_sel_hi:[1,0]
	v_pk_mul_f32 v[20:21], v[20:21], v[226:227] op_sel_hi:[1,0]
	v_pk_mul_f32 v[22:23], v[22:23], v[226:227] op_sel_hi:[1,0]
	v_pk_mul_f32 v[24:25], v[24:25], v[226:227] op_sel_hi:[1,0]
	v_pk_mul_f32 v[26:27], v[26:27], v[226:227] op_sel_hi:[1,0]
	v_pk_mul_f32 v[28:29], v[28:29], v[226:227] op_sel_hi:[1,0]
	v_pk_mul_f32 v[30:31], v[30:31], v[226:227] op_sel_hi:[1,0]
	v_pk_mul_f32 v[32:33], v[32:33], v[226:227] op_sel_hi:[1,0]
	v_pk_mul_f32 v[34:35], v[34:35], v[226:227] op_sel_hi:[1,0]
	v_pk_mul_f32 v[36:37], v[36:37], v[226:227] op_sel_hi:[1,0]
	v_pk_mul_f32 v[38:39], v[38:39], v[226:227] op_sel_hi:[1,0]
	v_pk_mul_f32 v[40:41], v[40:41], v[226:227] op_sel_hi:[1,0]
	v_pk_mul_f32 v[42:43], v[42:43], v[226:227] op_sel_hi:[1,0]
	v_pk_mul_f32 v[44:45], v[44:45], v[226:227] op_sel_hi:[1,0]
	v_pk_mul_f32 v[46:47], v[46:47], v[226:227] op_sel_hi:[1,0]
	v_sub_f32_e32 v0, 0, v245
	v_mov_b32_e32 v1, v0
	v_mov_b32_e32 v2, v0
	v_mov_b32_e32 v3, v0
	v_mov_b32_e32 v4, v0
	v_mov_b32_e32 v5, v0
	v_mov_b32_e32 v6, v0
	v_mov_b32_e32 v7, v0
	v_mov_b32_e32 v8, v0
	v_mov_b32_e32 v9, v0
	v_mov_b32_e32 v10, v0
	v_mov_b32_e32 v11, v0
	v_mov_b32_e32 v12, v0
	v_mov_b32_e32 v13, v0
	v_mov_b32_e32 v14, v0
	v_mov_b32_e32 v15, v0
.La_exp:
	v_exp_f32_e32 v148, v148
	v_exp_f32_e32 v149, v149
	v_exp_f32_e32 v150, v150
	v_exp_f32_e32 v151, v151
	v_exp_f32_e32 v152, v152
	v_exp_f32_e32 v153, v153
	v_exp_f32_e32 v154, v154
	v_exp_f32_e32 v155, v155
	v_add_f32_e32 v226, v148, v149
	v_add_f32_e32 v226, v226, v150
	v_add_f32_e32 v226, v226, v151
	v_add_f32_e32 v226, v226, v152
	v_add_f32_e32 v226, v226, v153
	v_add_f32_e32 v226, v226, v154
	v_add_f32_e32 v226, v226, v155
	v_cvt_pk_bf16_f32 v148, v148, v149
	v_cvt_pk_bf16_f32 v149, v150, v151
	v_cvt_pk_bf16_f32 v150, v152, v153
	v_cvt_pk_bf16_f32 v151, v154, v155
	s_waitcnt lgkmcnt(1)
	s_nop 0
	v_mfma_f32_32x32x16_bf16 v[48:63], v[96:99], v[148:151], v[48:63]
	v_mfma_f32_32x32x16_bf16 v[64:79], v[246:249], v[148:151], v[64:79]
	v_exp_f32_e32 v116, v116
	v_exp_f32_e32 v117, v117
	v_exp_f32_e32 v118, v118
	v_exp_f32_e32 v119, v119
	v_exp_f32_e32 v120, v120
	v_exp_f32_e32 v121, v121
	v_exp_f32_e32 v122, v122
	v_exp_f32_e32 v123, v123
	v_add_f32_e32 v227, v116, v117
	v_add_f32_e32 v227, v227, v118
	v_add_f32_e32 v227, v227, v119
	v_add_f32_e32 v227, v227, v120
	v_add_f32_e32 v227, v227, v121
	v_add_f32_e32 v227, v227, v122
	v_add_f32_e32 v227, v227, v123
	v_cvt_pk_bf16_f32 v116, v116, v117
	v_cvt_pk_bf16_f32 v117, v118, v119
	v_cvt_pk_bf16_f32 v118, v120, v121
	v_cvt_pk_bf16_f32 v119, v122, v123
	s_nop 1
	v_mfma_f32_32x32x16_bf16 v[16:31], v[96:99], v[116:119], v[16:31]
	v_mfma_f32_32x32x16_bf16 v[32:47], v[246:249], v[116:119], v[32:47]
	ds_read_b128 v[96:99], v237 offset:17952
	ds_read_b128 v[246:249], v237 offset:13376
	v_exp_f32_e32 v156, v156
	v_exp_f32_e32 v157, v157
	v_exp_f32_e32 v158, v158
	v_exp_f32_e32 v159, v159
	v_exp_f32_e32 v160, v160
	v_exp_f32_e32 v161, v161
	v_exp_f32_e32 v162, v162
	v_exp_f32_e32 v163, v163
	v_add_f32_e32 v226, v226, v156
	v_add_f32_e32 v226, v226, v157
	v_add_f32_e32 v226, v226, v158
	v_add_f32_e32 v226, v226, v159
	v_add_f32_e32 v226, v226, v160
	v_add_f32_e32 v226, v226, v161
	v_add_f32_e32 v226, v226, v162
	v_add_f32_e32 v226, v226, v163
	v_cvt_pk_bf16_f32 v156, v156, v157
	v_cvt_pk_bf16_f32 v157, v158, v159
	v_cvt_pk_bf16_f32 v158, v160, v161
	v_cvt_pk_bf16_f32 v159, v162, v163
	s_waitcnt lgkmcnt(1)
	s_nop 0
	v_mfma_f32_32x32x16_bf16 v[48:63], v[250:253], v[156:159], v[48:63]
	v_mfma_f32_32x32x16_bf16 v[64:79], v[96:99], v[156:159], v[64:79]
	v_exp_f32_e32 v124, v124
	v_exp_f32_e32 v125, v125
	v_exp_f32_e32 v126, v126
	v_exp_f32_e32 v127, v127
	v_exp_f32_e32 v128, v128
	v_exp_f32_e32 v129, v129
	v_exp_f32_e32 v130, v130
	v_exp_f32_e32 v131, v131
	v_add_f32_e32 v227, v227, v124
	v_add_f32_e32 v227, v227, v125
	v_add_f32_e32 v227, v227, v126
	v_add_f32_e32 v227, v227, v127
	v_add_f32_e32 v227, v227, v128
	v_add_f32_e32 v227, v227, v129
	v_add_f32_e32 v227, v227, v130
	v_add_f32_e32 v227, v227, v131
	v_cvt_pk_bf16_f32 v124, v124, v125
	v_cvt_pk_bf16_f32 v125, v126, v127
	v_cvt_pk_bf16_f32 v126, v128, v129
	v_cvt_pk_bf16_f32 v127, v130, v131
	s_nop 1
	v_mfma_f32_32x32x16_bf16 v[16:31], v[250:253], v[124:127], v[16:31]
	v_mfma_f32_32x32x16_bf16 v[32:47], v[96:99], v[124:127], v[32:47]
	ds_read_b128 v[250:253], v237 offset:17984
	ds_read_b128 v[96:99], v237 offset:13408
	v_exp_f32_e32 v80, v80
	v_exp_f32_e32 v81, v81
	v_exp_f32_e32 v82, v82
	v_exp_f32_e32 v83, v83
	v_exp_f32_e32 v84, v84
	v_exp_f32_e32 v85, v85
	v_exp_f32_e32 v86, v86
	v_exp_f32_e32 v87, v87
	v_add_f32_e32 v226, v226, v80
	v_add_f32_e32 v226, v226, v81
	v_add_f32_e32 v226, v226, v82
	v_add_f32_e32 v226, v226, v83
	v_add_f32_e32 v226, v226, v84
	v_add_f32_e32 v226, v226, v85
	v_add_f32_e32 v226, v226, v86
	v_add_f32_e32 v226, v226, v87
	v_cvt_pk_bf16_f32 v80, v80, v81
	v_cvt_pk_bf16_f32 v81, v82, v83
	v_cvt_pk_bf16_f32 v82, v84, v85
	v_cvt_pk_bf16_f32 v83, v86, v87
	s_waitcnt lgkmcnt(1)
	s_nop 0
	v_mfma_f32_32x32x16_bf16 v[48:63], v[246:249], v[80:83], v[48:63]
	v_mfma_f32_32x32x16_bf16 v[64:79], v[250:253], v[80:83], v[64:79]
	v_exp_f32_e32 v132, v132
	v_exp_f32_e32 v133, v133
	v_exp_f32_e32 v134, v134
	v_exp_f32_e32 v135, v135
	v_exp_f32_e32 v136, v136
	v_exp_f32_e32 v137, v137
	v_exp_f32_e32 v138, v138
	v_exp_f32_e32 v139, v139
	v_add_f32_e32 v227, v227, v132
	v_add_f32_e32 v227, v227, v133
	v_add_f32_e32 v227, v227, v134
	v_add_f32_e32 v227, v227, v135
	v_add_f32_e32 v227, v227, v136
	v_add_f32_e32 v227, v227, v137
	v_add_f32_e32 v227, v227, v138
	v_add_f32_e32 v227, v227, v139
	v_cvt_pk_bf16_f32 v132, v132, v133
	v_cvt_pk_bf16_f32 v133, v134, v135
	v_cvt_pk_bf16_f32 v134, v136, v137
	v_cvt_pk_bf16_f32 v135, v138, v139
	s_nop 1
	v_mfma_f32_32x32x16_bf16 v[16:31], v[246:249], v[132:135], v[16:31]
	v_mfma_f32_32x32x16_bf16 v[32:47], v[250:253], v[132:135], v[32:47]
	ds_read_b128 v[246:249], v237 offset:18016
	v_exp_f32_e32 v88, v88
	v_exp_f32_e32 v89, v89
	v_exp_f32_e32 v90, v90
	v_exp_f32_e32 v91, v91
	v_exp_f32_e32 v92, v92
	v_exp_f32_e32 v93, v93
	v_exp_f32_e32 v94, v94
	v_exp_f32_e32 v95, v95
	v_add_f32_e32 v226, v226, v88
	v_add_f32_e32 v226, v226, v89
	v_add_f32_e32 v226, v226, v90
	v_add_f32_e32 v226, v226, v91
	v_add_f32_e32 v226, v226, v92
	v_add_f32_e32 v226, v226, v93
	v_add_f32_e32 v226, v226, v94
	v_add_f32_e32 v226, v226, v95
	v_cvt_pk_bf16_f32 v88, v88, v89
	v_cvt_pk_bf16_f32 v89, v90, v91
	v_cvt_pk_bf16_f32 v90, v92, v93
	v_cvt_pk_bf16_f32 v91, v94, v95
	v_add_f32_e32 v243, v243, v226
	s_waitcnt lgkmcnt(0)
	s_nop 0
	v_mfma_f32_32x32x16_bf16 v[48:63], v[96:99], v[88:91], v[48:63]
	v_mfma_f32_32x32x16_bf16 v[64:79], v[246:249], v[88:91], v[64:79]
	v_exp_f32_e32 v140, v140
	v_exp_f32_e32 v141, v141
	v_exp_f32_e32 v142, v142
	v_exp_f32_e32 v143, v143
	v_exp_f32_e32 v144, v144
	v_exp_f32_e32 v145, v145
	v_exp_f32_e32 v146, v146
	v_exp_f32_e32 v147, v147
	v_add_f32_e32 v227, v227, v140
	v_add_f32_e32 v227, v227, v141
	v_add_f32_e32 v227, v227, v142
	v_add_f32_e32 v227, v227, v143
	v_add_f32_e32 v227, v227, v144
	v_add_f32_e32 v227, v227, v145
	v_add_f32_e32 v227, v227, v146
	v_add_f32_e32 v227, v227, v147
	v_cvt_pk_bf16_f32 v140, v140, v141
	v_cvt_pk_bf16_f32 v141, v142, v143
	v_cvt_pk_bf16_f32 v142, v144, v145
	v_cvt_pk_bf16_f32 v143, v146, v147
	v_add_f32_e32 v239, v239, v227
	s_nop 1
	v_mfma_f32_32x32x16_bf16 v[16:31], v[96:99], v[140:143], v[16:31]
	v_mfma_f32_32x32x16_bf16 v[32:47], v[246:249], v[140:143], v[32:47]
	s_andn2_b64 vcc, exec, s[78:79]
	s_cbranch_vccnz .LBB0_707
.LBB0_704:
	s_sub_i32 s73, 0, s95
	v_add_u32_e32 v225, s73, v236
	s_waitcnt vmcnt(1)
	ds_write_b128 v225, v[164:167] offset:22528
	s_and_saveexec_b64 s[78:79], s[6:7]
	v_add_u32_e32 v225, s73, v238
	ds_write_b128 v225, v[168:171] offset:22656
	s_or_b64 exec, exec, s[78:79]
	v_add_u32_e32 v225, s73, v240
	s_waitcnt vmcnt(0)
	ds_write_b128 v225, v[172:175] offset:35840
